# all row-store exchanges combined: P8 + P6 pass 1 and 2 (pass 2 now without SGPR constant) + P10 final output
# baseline (speedup 1.0000x reference)
.LBB0_1592:
	s_or_b64 exec, exec, s[48:49]
	s_waitcnt vmcnt(9)
	v_pk_add_f32 v[92:93], v[92:93], 1.0 op_sel_hi:[1,0]
	s_waitcnt lgkmcnt(0)
	v_pk_mul_f32 v[84:85], v[84:85], v[92:93]
	s_barrier
	v_and_b32_e32 v176, 15, v228
	v_lshrrev_b32_e32 v177, 6, v228
	v_lshrrev_b32_e32 v178, 3, v230
	v_and_b32_e32 v179, 7, v176
	v_xor_b32_e32 v179, v178, v179
	v_mul_u32_u24_e32 v180, 0x2400, v177
	v_add_u32_e32 v180, 0x20000, v180
	v_lshl_add_u32 v144, v176, 9, v180
	v_lshl_add_u32 v144, v179, 4, v144
	v_lshrrev_b32_e32 v181, 5, v230
	v_lshrrev_b32_e32 v182, 5, v236
	v_lshl_add_u32 v181, v181, 2, v182
	v_and_b32_e32 v182, 31, v236
	v_and_b32_e32 v183, 7, v181
	v_xor_b32_e32 v183, v182, v183
	v_lshl_add_u32 v145, v181, 9, v180
	v_lshl_add_u32 v145, v183, 4, v145
	v_add_u32_e32 v183, 2, v181
	v_lshl_add_u32 v146, v183, 9, v180
	v_and_b32_e32 v183, 7, v183
	v_xor_b32_e32 v183, v182, v183
	v_lshl_add_u32 v146, v183, 4, v146
	v_sub_u32_e32 v183, v181, v176
	v_lshlrev_b32_e32 v183, 11, v183
	v_lshlrev_b32_e32 v182, 3, v182
	v_sub_u32_e32 v182, v182, v230
	v_lshl_add_u32 v148, v182, 1, v183
	v_add_u32_e32 v148, 0x800, v148
	v_ashrrev_i32_e32 v149, 31, v148
	ds_read_b32 v92, v232
	s_waitcnt vmcnt(8)
	v_pk_add_f32 v[90:91], v[90:91], 1.0 op_sel_hi:[1,0]
	v_pk_add_f32 v[88:89], v[88:89], 1.0 op_sel_hi:[1,0]
	v_pk_add_f32 v[94:95], v[94:95], 1.0 op_sel_hi:[1,0]
	v_pk_mul_f32 v[82:83], v[82:83], v[90:91]
	v_pk_mul_f32 v[80:81], v[80:81], v[88:89]
	v_lshlrev_b32_e32 v88, 16, v8
	v_and_b32_e32 v89, 0xffff0000, v8
	v_lshlrev_b32_e32 v8, 16, v9
	v_and_b32_e32 v9, 0xffff0000, v9
	v_lshlrev_b32_e32 v90, 16, v10
	v_and_b32_e32 v91, 0xffff0000, v10
	v_lshlrev_b32_e32 v10, 16, v11
	v_and_b32_e32 v11, 0xffff0000, v11
	v_pk_mul_f32 v[86:87], v[86:87], v[94:95]
	s_waitcnt lgkmcnt(0)
	v_pk_mul_f32 v[88:89], v[92:93], v[88:89] op_sel_hi:[0,1]
	v_pk_mul_f32 v[8:9], v[92:93], v[8:9] op_sel_hi:[0,1]
	v_pk_mul_f32 v[90:91], v[92:93], v[90:91] op_sel_hi:[0,1]
	v_pk_mul_f32 v[10:11], v[92:93], v[10:11] op_sel_hi:[0,1]
	s_waitcnt vmcnt(6)
	v_pk_fma_f32 v[8:9], v[82:83], v[8:9], v[78:79]
	v_pk_fma_f32 v[88:89], v[80:81], v[88:89], v[76:77]
	v_pk_fma_f32 v[10:11], v[86:87], v[10:11], v[74:75]
	v_pk_fma_f32 v[90:91], v[84:85], v[90:91], v[72:73]
	v_cvt_pk_bf16_f32 v88, v88, v89
	v_cvt_pk_bf16_f32 v89, v8, v9
	v_lshlrev_b64 v[8:9], 1, v[208:209]
	v_cvt_pk_bf16_f32 v90, v90, v91
	v_cvt_pk_bf16_f32 v91, v10, v11
	v_lshl_add_u64 v[10:11], s[10:11], 0, v[212:213]
	v_lshl_add_u64 v[10:11], v[10:11], 0, v[8:9]
	s_waitcnt vmcnt(2)
	v_pk_add_f32 v[106:107], v[106:107], 1.0 op_sel_hi:[1,0]
	v_pk_add_f32 v[104:105], v[104:105], 1.0 op_sel_hi:[1,0]
	ds_write_b128 v144, v[88:91]
	v_pk_add_f32 v[110:111], v[110:111], 1.0 op_sel_hi:[1,0]
	v_pk_add_f32 v[108:109], v[108:109], 1.0 op_sel_hi:[1,0]
	v_lshlrev_b32_e32 v88, 16, v4
	v_and_b32_e32 v89, 0xffff0000, v4
	v_lshlrev_b32_e32 v4, 16, v5
	v_and_b32_e32 v5, 0xffff0000, v5
	v_pk_mul_f32 v[98:99], v[98:99], v[106:107]
	v_pk_mul_f32 v[96:97], v[96:97], v[104:105]
	v_lshlrev_b32_e32 v90, 16, v6
	v_and_b32_e32 v91, 0xffff0000, v6
	v_lshlrev_b32_e32 v6, 16, v7
	v_and_b32_e32 v7, 0xffff0000, v7
	v_pk_mul_f32 v[88:89], v[92:93], v[88:89] op_sel_hi:[0,1]
	v_pk_mul_f32 v[4:5], v[92:93], v[4:5] op_sel_hi:[0,1]
	v_pk_mul_f32 v[100:101], v[100:101], v[108:109]
	v_pk_mul_f32 v[102:103], v[102:103], v[110:111]
	s_waitcnt vmcnt(0)
	v_pk_fma_f32 v[94:95], v[98:99], v[4:5], v[66:67]
	v_pk_fma_f32 v[4:5], v[96:97], v[88:89], v[64:65]
	v_pk_mul_f32 v[88:89], v[92:93], v[90:91] op_sel_hi:[0,1]
	v_pk_mul_f32 v[6:7], v[92:93], v[6:7] op_sel_hi:[0,1]
	v_pk_fma_f32 v[90:91], v[102:103], v[6:7], v[42:43]
	v_pk_fma_f32 v[6:7], v[100:101], v[88:89], v[40:41]
	v_cvt_pk_bf16_f32 v4, v4, v5
	v_cvt_pk_bf16_f32 v5, v94, v95
	s_andn2_b64 vcc, exec, s[4:5]
	v_cvt_pk_bf16_f32 v6, v6, v7
	v_cvt_pk_bf16_f32 v7, v90, v91
	ds_write_b128 v144, v[4:7] offset:256
	v_lshl_add_u64 v[150:151], v[10:11], 0, v[148:149]
	s_waitcnt lgkmcnt(0)
	s_barrier
	ds_read_b128 v[168:171], v145
	ds_read_b128 v[172:175], v146
	s_waitcnt lgkmcnt(0)
	s_barrier
	global_store_dwordx4 v[150:151], v[168:171], off offset:-2048
	global_store_dwordx4 v[150:151], v[172:175], off offset:2048
	ds_read_b32 v4, v232 offset:64
	v_lshlrev_b32_e32 v10, 16, v2
	v_lshlrev_b32_e32 v6, 16, v0
	v_and_b32_e32 v7, 0xffff0000, v0
	v_lshlrev_b32_e32 v0, 16, v1
	v_and_b32_e32 v1, 0xffff0000, v1
	v_and_b32_e32 v11, 0xffff0000, v2
	v_lshlrev_b32_e32 v2, 16, v3
	v_and_b32_e32 v3, 0xffff0000, v3
	s_waitcnt lgkmcnt(0)
	v_pk_mul_f32 v[6:7], v[4:5], v[6:7] op_sel_hi:[0,1]
	v_pk_mul_f32 v[0:1], v[4:5], v[0:1] op_sel_hi:[0,1]
	v_pk_fma_f32 v[88:89], v[82:83], v[0:1], v[78:79]
	v_pk_fma_f32 v[0:1], v[80:81], v[6:7], v[76:77]
	v_pk_mul_f32 v[6:7], v[4:5], v[10:11] op_sel_hi:[0,1]
	v_pk_mul_f32 v[2:3], v[4:5], v[2:3] op_sel_hi:[0,1]
	v_pk_fma_f32 v[10:11], v[86:87], v[2:3], v[74:75]
	v_pk_fma_f32 v[2:3], v[84:85], v[6:7], v[72:73]
	v_lshl_add_u64 v[6:7], s[10:11], 0, v[210:211]
	v_cvt_pk_bf16_f32 v0, v0, v1
	v_cvt_pk_bf16_f32 v1, v88, v89
	v_cvt_pk_bf16_f32 v2, v2, v3
	v_cvt_pk_bf16_f32 v3, v10, v11
	v_lshl_add_u64 v[6:7], v[6:7], 0, v[8:9]
	ds_write_b128 v144, v[0:3]
	v_lshlrev_b32_e32 v10, 16, v14
	v_and_b32_e32 v11, 0xffff0000, v14
	v_lshlrev_b32_e32 v0, 16, v12
	v_and_b32_e32 v1, 0xffff0000, v12
	v_lshlrev_b32_e32 v2, 16, v13
	v_and_b32_e32 v3, 0xffff0000, v13
	v_lshlrev_b32_e32 v12, 16, v15
	v_and_b32_e32 v13, 0xffff0000, v15
	v_pk_mul_f32 v[0:1], v[4:5], v[0:1] op_sel_hi:[0,1]
	v_pk_mul_f32 v[2:3], v[4:5], v[2:3] op_sel_hi:[0,1]
	v_pk_mul_f32 v[10:11], v[4:5], v[10:11] op_sel_hi:[0,1]
	v_pk_mul_f32 v[4:5], v[4:5], v[12:13] op_sel_hi:[0,1]
	v_pk_fma_f32 v[2:3], v[98:99], v[2:3], v[66:67]
	v_pk_fma_f32 v[0:1], v[96:97], v[0:1], v[64:65]
	v_pk_fma_f32 v[4:5], v[102:103], v[4:5], v[42:43]
	v_pk_fma_f32 v[10:11], v[100:101], v[10:11], v[40:41]
	v_cvt_pk_bf16_f32 v0, v0, v1
	v_cvt_pk_bf16_f32 v1, v2, v3
	v_lshlrev_b32_e32 v12, 16, v27
	v_cvt_pk_bf16_f32 v2, v10, v11
	v_cvt_pk_bf16_f32 v3, v4, v5
	ds_read_b32 v4, v232 offset:128
	ds_write_b128 v144, v[0:3] offset:256
	v_lshl_add_u64 v[150:151], v[6:7], 0, v[148:149]
	s_waitcnt lgkmcnt(0)
	s_barrier
	ds_read_b128 v[168:171], v145
	ds_read_b128 v[172:175], v146
	s_waitcnt lgkmcnt(0)
	s_barrier
	global_store_dwordx4 v[150:151], v[168:171], off offset:-2048
	global_store_dwordx4 v[150:151], v[172:175], off offset:2048
	v_lshlrev_b32_e32 v6, 16, v18
	v_and_b32_e32 v7, 0xffff0000, v18
	v_lshlrev_b32_e32 v0, 16, v16
	v_and_b32_e32 v1, 0xffff0000, v16
	v_lshlrev_b32_e32 v2, 16, v17
	v_and_b32_e32 v3, 0xffff0000, v17
	s_waitcnt lgkmcnt(0)
	v_pk_mul_f32 v[0:1], v[4:5], v[0:1] op_sel_hi:[0,1]
	v_pk_mul_f32 v[2:3], v[4:5], v[2:3] op_sel_hi:[0,1]
	v_pk_mul_f32 v[6:7], v[4:5], v[6:7] op_sel_hi:[0,1]
	v_lshlrev_b32_e32 v10, 16, v19
	v_and_b32_e32 v11, 0xffff0000, v19
	v_pk_fma_f32 v[2:3], v[82:83], v[2:3], v[78:79]
	v_pk_fma_f32 v[0:1], v[80:81], v[0:1], v[76:77]
	v_pk_fma_f32 v[6:7], v[84:85], v[6:7], v[72:73]
	v_pk_mul_f32 v[10:11], v[4:5], v[10:11] op_sel_hi:[0,1]
	v_cvt_pk_bf16_f32 v0, v0, v1
	v_cvt_pk_bf16_f32 v1, v2, v3
	v_cvt_pk_bf16_f32 v2, v6, v7
	v_lshl_add_u64 v[6:7], s[10:11], 0, v[214:215]
	v_pk_fma_f32 v[10:11], v[86:87], v[10:11], v[74:75]
	v_lshl_add_u64 v[6:7], v[6:7], 0, v[8:9]
	v_cvt_pk_bf16_f32 v3, v10, v11
	ds_write_b128 v144, v[0:3]
	v_lshlrev_b32_e32 v10, 16, v26
	v_and_b32_e32 v11, 0xffff0000, v26
	v_lshlrev_b32_e32 v0, 16, v24
	v_and_b32_e32 v1, 0xffff0000, v24
	v_lshlrev_b32_e32 v2, 16, v25
	v_and_b32_e32 v3, 0xffff0000, v25
	v_and_b32_e32 v13, 0xffff0000, v27
	v_pk_mul_f32 v[0:1], v[4:5], v[0:1] op_sel_hi:[0,1]
	v_pk_mul_f32 v[2:3], v[4:5], v[2:3] op_sel_hi:[0,1]
	v_pk_mul_f32 v[10:11], v[4:5], v[10:11] op_sel_hi:[0,1]
	v_pk_mul_f32 v[4:5], v[4:5], v[12:13] op_sel_hi:[0,1]
	v_pk_fma_f32 v[2:3], v[98:99], v[2:3], v[66:67]
	v_pk_fma_f32 v[0:1], v[96:97], v[0:1], v[64:65]
	v_pk_fma_f32 v[4:5], v[102:103], v[4:5], v[42:43]
	v_pk_fma_f32 v[10:11], v[100:101], v[10:11], v[40:41]
	v_cvt_pk_bf16_f32 v0, v0, v1
	v_cvt_pk_bf16_f32 v1, v2, v3
	v_lshlrev_b32_e32 v12, 16, v31
	v_cvt_pk_bf16_f32 v2, v10, v11
	v_cvt_pk_bf16_f32 v3, v4, v5
	ds_read_b32 v4, v232 offset:192
	ds_write_b128 v144, v[0:3] offset:256
	v_lshl_add_u64 v[150:151], v[6:7], 0, v[148:149]
	s_waitcnt lgkmcnt(0)
	s_barrier
	ds_read_b128 v[168:171], v145
	ds_read_b128 v[172:175], v146
	s_waitcnt lgkmcnt(0)
	s_barrier
	global_store_dwordx4 v[150:151], v[168:171], off offset:-2048
	global_store_dwordx4 v[150:151], v[172:175], off offset:2048
	v_lshlrev_b32_e32 v6, 16, v22
	v_and_b32_e32 v7, 0xffff0000, v22
	v_lshlrev_b32_e32 v0, 16, v20
	v_and_b32_e32 v1, 0xffff0000, v20
	v_lshlrev_b32_e32 v2, 16, v21
	v_and_b32_e32 v3, 0xffff0000, v21
	s_waitcnt lgkmcnt(0)
	v_pk_mul_f32 v[0:1], v[4:5], v[0:1] op_sel_hi:[0,1]
	v_pk_mul_f32 v[2:3], v[4:5], v[2:3] op_sel_hi:[0,1]
	v_pk_mul_f32 v[6:7], v[4:5], v[6:7] op_sel_hi:[0,1]
	v_lshlrev_b32_e32 v10, 16, v23
	v_and_b32_e32 v11, 0xffff0000, v23
	v_pk_fma_f32 v[2:3], v[82:83], v[2:3], v[78:79]
	v_pk_fma_f32 v[0:1], v[80:81], v[0:1], v[76:77]
	v_pk_fma_f32 v[6:7], v[84:85], v[6:7], v[72:73]
	v_pk_mul_f32 v[10:11], v[4:5], v[10:11] op_sel_hi:[0,1]
	v_cvt_pk_bf16_f32 v0, v0, v1
	v_cvt_pk_bf16_f32 v1, v2, v3
	v_cvt_pk_bf16_f32 v2, v6, v7
	v_lshl_add_u64 v[6:7], s[10:11], 0, v[160:161]
	v_pk_fma_f32 v[10:11], v[86:87], v[10:11], v[74:75]
	v_lshl_add_u64 v[6:7], v[6:7], 0, v[8:9]
	v_cvt_pk_bf16_f32 v3, v10, v11
	ds_write_b128 v144, v[0:3]
	v_lshlrev_b32_e32 v10, 16, v30
	v_and_b32_e32 v11, 0xffff0000, v30
	v_lshlrev_b32_e32 v0, 16, v28
	v_and_b32_e32 v1, 0xffff0000, v28
	v_lshlrev_b32_e32 v2, 16, v29
	v_and_b32_e32 v3, 0xffff0000, v29
	v_and_b32_e32 v13, 0xffff0000, v31
	v_pk_mul_f32 v[0:1], v[4:5], v[0:1] op_sel_hi:[0,1]
	v_pk_mul_f32 v[2:3], v[4:5], v[2:3] op_sel_hi:[0,1]
	v_pk_mul_f32 v[10:11], v[4:5], v[10:11] op_sel_hi:[0,1]
	v_pk_mul_f32 v[4:5], v[4:5], v[12:13] op_sel_hi:[0,1]
	v_pk_fma_f32 v[2:3], v[98:99], v[2:3], v[66:67]
	v_pk_fma_f32 v[0:1], v[96:97], v[0:1], v[64:65]
	v_pk_fma_f32 v[4:5], v[102:103], v[4:5], v[42:43]
	v_pk_fma_f32 v[10:11], v[100:101], v[10:11], v[40:41]
	v_cvt_pk_bf16_f32 v0, v0, v1
	v_cvt_pk_bf16_f32 v1, v2, v3
	v_lshlrev_b32_e32 v12, 16, v51
	v_cvt_pk_bf16_f32 v2, v10, v11
	v_cvt_pk_bf16_f32 v3, v4, v5
	ds_read_b32 v4, v232 offset:512
	ds_write_b128 v144, v[0:3] offset:256
	v_lshl_add_u64 v[150:151], v[6:7], 0, v[148:149]
	s_waitcnt lgkmcnt(0)
	s_barrier
	ds_read_b128 v[168:171], v145
	ds_read_b128 v[172:175], v146
	s_waitcnt lgkmcnt(0)
	s_barrier
	global_store_dwordx4 v[150:151], v[168:171], off offset:-2048
	global_store_dwordx4 v[150:151], v[172:175], off offset:2048
	v_lshlrev_b32_e32 v6, 16, v34
	v_and_b32_e32 v7, 0xffff0000, v34
	v_lshlrev_b32_e32 v0, 16, v32
	v_and_b32_e32 v1, 0xffff0000, v32
	v_lshlrev_b32_e32 v2, 16, v33
	v_and_b32_e32 v3, 0xffff0000, v33
	s_waitcnt lgkmcnt(0)
	v_pk_mul_f32 v[0:1], v[4:5], v[0:1] op_sel_hi:[0,1]
	v_pk_mul_f32 v[2:3], v[4:5], v[2:3] op_sel_hi:[0,1]
	v_pk_mul_f32 v[6:7], v[4:5], v[6:7] op_sel_hi:[0,1]
	v_lshlrev_b32_e32 v10, 16, v35
	v_and_b32_e32 v11, 0xffff0000, v35
	v_pk_fma_f32 v[2:3], v[82:83], v[2:3], v[78:79]
	v_pk_fma_f32 v[0:1], v[80:81], v[0:1], v[76:77]
	v_pk_fma_f32 v[6:7], v[84:85], v[6:7], v[72:73]
	v_pk_mul_f32 v[10:11], v[4:5], v[10:11] op_sel_hi:[0,1]
	v_cvt_pk_bf16_f32 v0, v0, v1
	v_cvt_pk_bf16_f32 v1, v2, v3
	v_cvt_pk_bf16_f32 v2, v6, v7
	v_lshl_add_u64 v[6:7], s[10:11], 0, v[162:163]
	v_pk_fma_f32 v[10:11], v[86:87], v[10:11], v[74:75]
	v_lshl_add_u64 v[6:7], v[6:7], 0, v[8:9]
	v_cvt_pk_bf16_f32 v3, v10, v11
	ds_write_b128 v144, v[0:3]
	v_lshlrev_b32_e32 v10, 16, v50
	v_and_b32_e32 v11, 0xffff0000, v50
	v_lshlrev_b32_e32 v0, 16, v48
	v_and_b32_e32 v1, 0xffff0000, v48
	v_lshlrev_b32_e32 v2, 16, v49
	v_and_b32_e32 v3, 0xffff0000, v49
	v_and_b32_e32 v13, 0xffff0000, v51
	v_pk_mul_f32 v[0:1], v[4:5], v[0:1] op_sel_hi:[0,1]
	v_pk_mul_f32 v[2:3], v[4:5], v[2:3] op_sel_hi:[0,1]
	v_pk_mul_f32 v[10:11], v[4:5], v[10:11] op_sel_hi:[0,1]
	v_pk_mul_f32 v[4:5], v[4:5], v[12:13] op_sel_hi:[0,1]
	v_pk_fma_f32 v[2:3], v[98:99], v[2:3], v[66:67]
	v_pk_fma_f32 v[0:1], v[96:97], v[0:1], v[64:65]
	v_pk_fma_f32 v[4:5], v[102:103], v[4:5], v[42:43]
	v_pk_fma_f32 v[10:11], v[100:101], v[10:11], v[40:41]
	v_cvt_pk_bf16_f32 v0, v0, v1
	v_cvt_pk_bf16_f32 v1, v2, v3
	v_lshlrev_b32_e32 v12, 16, v55
	v_cvt_pk_bf16_f32 v2, v10, v11
	v_cvt_pk_bf16_f32 v3, v4, v5
	ds_read_b32 v4, v232 offset:576
	ds_write_b128 v144, v[0:3] offset:256
	v_lshl_add_u64 v[150:151], v[6:7], 0, v[148:149]
	s_waitcnt lgkmcnt(0)
	s_barrier
	ds_read_b128 v[168:171], v145
	ds_read_b128 v[172:175], v146
	s_waitcnt lgkmcnt(0)
	s_barrier
	global_store_dwordx4 v[150:151], v[168:171], off offset:-2048
	global_store_dwordx4 v[150:151], v[172:175], off offset:2048
	v_lshlrev_b32_e32 v6, 16, v46
	v_and_b32_e32 v7, 0xffff0000, v46
	v_lshlrev_b32_e32 v0, 16, v44
	v_and_b32_e32 v1, 0xffff0000, v44
	v_lshlrev_b32_e32 v2, 16, v45
	v_and_b32_e32 v3, 0xffff0000, v45
	s_waitcnt lgkmcnt(0)
	v_pk_mul_f32 v[0:1], v[4:5], v[0:1] op_sel_hi:[0,1]
	v_pk_mul_f32 v[2:3], v[4:5], v[2:3] op_sel_hi:[0,1]
	v_pk_mul_f32 v[6:7], v[4:5], v[6:7] op_sel_hi:[0,1]
	v_lshlrev_b32_e32 v10, 16, v47
	v_and_b32_e32 v11, 0xffff0000, v47
	v_pk_fma_f32 v[2:3], v[82:83], v[2:3], v[78:79]
	v_pk_fma_f32 v[0:1], v[80:81], v[0:1], v[76:77]
	v_pk_fma_f32 v[6:7], v[84:85], v[6:7], v[72:73]
	v_pk_mul_f32 v[10:11], v[4:5], v[10:11] op_sel_hi:[0,1]
	v_cvt_pk_bf16_f32 v0, v0, v1
	v_cvt_pk_bf16_f32 v1, v2, v3
	v_cvt_pk_bf16_f32 v2, v6, v7
	v_lshl_add_u64 v[6:7], s[10:11], 0, v[164:165]
	v_pk_fma_f32 v[10:11], v[86:87], v[10:11], v[74:75]
	v_lshl_add_u64 v[6:7], v[6:7], 0, v[8:9]
	v_cvt_pk_bf16_f32 v3, v10, v11
	ds_write_b128 v144, v[0:3]
	v_lshlrev_b32_e32 v10, 16, v54
	v_and_b32_e32 v11, 0xffff0000, v54
	v_lshlrev_b32_e32 v0, 16, v52
	v_and_b32_e32 v1, 0xffff0000, v52
	v_lshlrev_b32_e32 v2, 16, v53
	v_and_b32_e32 v3, 0xffff0000, v53
	v_and_b32_e32 v13, 0xffff0000, v55
	v_pk_mul_f32 v[0:1], v[4:5], v[0:1] op_sel_hi:[0,1]
	v_pk_mul_f32 v[2:3], v[4:5], v[2:3] op_sel_hi:[0,1]
	v_pk_mul_f32 v[10:11], v[4:5], v[10:11] op_sel_hi:[0,1]
	v_pk_mul_f32 v[4:5], v[4:5], v[12:13] op_sel_hi:[0,1]
	v_pk_fma_f32 v[2:3], v[98:99], v[2:3], v[66:67]
	v_pk_fma_f32 v[0:1], v[96:97], v[0:1], v[64:65]
	v_pk_fma_f32 v[4:5], v[102:103], v[4:5], v[42:43]
	v_pk_fma_f32 v[10:11], v[100:101], v[10:11], v[40:41]
	v_cvt_pk_bf16_f32 v0, v0, v1
	v_cvt_pk_bf16_f32 v1, v2, v3
	v_lshlrev_b32_e32 v12, 16, v71
	v_cvt_pk_bf16_f32 v2, v10, v11
	v_cvt_pk_bf16_f32 v3, v4, v5
	ds_read_b32 v4, v232 offset:640
	ds_write_b128 v144, v[0:3] offset:256
	v_lshl_add_u64 v[150:151], v[6:7], 0, v[148:149]
	s_waitcnt lgkmcnt(0)
	s_barrier
	ds_read_b128 v[168:171], v145
	ds_read_b128 v[172:175], v146
	s_waitcnt lgkmcnt(0)
	s_barrier
	global_store_dwordx4 v[150:151], v[168:171], off offset:-2048
	global_store_dwordx4 v[150:151], v[172:175], off offset:2048
	v_lshlrev_b32_e32 v6, 16, v58
	v_and_b32_e32 v7, 0xffff0000, v58
	v_lshlrev_b32_e32 v0, 16, v56
	v_and_b32_e32 v1, 0xffff0000, v56
	v_lshlrev_b32_e32 v2, 16, v57
	v_and_b32_e32 v3, 0xffff0000, v57
	s_waitcnt lgkmcnt(0)
	v_pk_mul_f32 v[0:1], v[4:5], v[0:1] op_sel_hi:[0,1]
	v_pk_mul_f32 v[2:3], v[4:5], v[2:3] op_sel_hi:[0,1]
	v_pk_mul_f32 v[6:7], v[4:5], v[6:7] op_sel_hi:[0,1]
	v_lshlrev_b32_e32 v10, 16, v59
	v_and_b32_e32 v11, 0xffff0000, v59
	v_pk_fma_f32 v[2:3], v[82:83], v[2:3], v[78:79]
	v_pk_fma_f32 v[0:1], v[80:81], v[0:1], v[76:77]
	v_pk_fma_f32 v[6:7], v[84:85], v[6:7], v[72:73]
	v_pk_mul_f32 v[10:11], v[4:5], v[10:11] op_sel_hi:[0,1]
	v_cvt_pk_bf16_f32 v0, v0, v1
	v_cvt_pk_bf16_f32 v1, v2, v3
	v_cvt_pk_bf16_f32 v2, v6, v7
	v_lshl_add_u64 v[6:7], s[10:11], 0, v[120:121]
	v_pk_fma_f32 v[10:11], v[86:87], v[10:11], v[74:75]
	v_lshl_add_u64 v[6:7], v[6:7], 0, v[8:9]
	v_cvt_pk_bf16_f32 v3, v10, v11
	ds_write_b128 v144, v[0:3]
	v_lshlrev_b32_e32 v10, 16, v70
	v_and_b32_e32 v11, 0xffff0000, v70
	v_lshlrev_b32_e32 v0, 16, v68
	v_and_b32_e32 v1, 0xffff0000, v68
	v_lshlrev_b32_e32 v2, 16, v69
	v_and_b32_e32 v3, 0xffff0000, v69
	v_and_b32_e32 v13, 0xffff0000, v71
	v_pk_mul_f32 v[0:1], v[4:5], v[0:1] op_sel_hi:[0,1]
	v_pk_mul_f32 v[2:3], v[4:5], v[2:3] op_sel_hi:[0,1]
	v_pk_mul_f32 v[10:11], v[4:5], v[10:11] op_sel_hi:[0,1]
	v_pk_mul_f32 v[4:5], v[4:5], v[12:13] op_sel_hi:[0,1]
	v_pk_fma_f32 v[2:3], v[98:99], v[2:3], v[66:67]
	v_pk_fma_f32 v[0:1], v[96:97], v[0:1], v[64:65]
	v_pk_fma_f32 v[4:5], v[102:103], v[4:5], v[42:43]
	v_pk_fma_f32 v[10:11], v[100:101], v[10:11], v[40:41]
	v_cvt_pk_bf16_f32 v0, v0, v1
	v_cvt_pk_bf16_f32 v1, v2, v3
	s_mov_b64 s[4:5], -1
	v_cvt_pk_bf16_f32 v2, v10, v11
	v_cvt_pk_bf16_f32 v3, v4, v5
	ds_read_b32 v4, v232 offset:704
	ds_write_b128 v144, v[0:3] offset:256
	v_lshl_add_u64 v[150:151], v[6:7], 0, v[148:149]
	s_waitcnt lgkmcnt(0)
	s_barrier
	ds_read_b128 v[168:171], v145
	ds_read_b128 v[172:175], v146
	s_waitcnt lgkmcnt(0)
	s_barrier
	global_store_dwordx4 v[150:151], v[168:171], off offset:-2048
	global_store_dwordx4 v[150:151], v[172:175], off offset:2048
	v_lshlrev_b32_e32 v6, 16, v62
	v_and_b32_e32 v7, 0xffff0000, v62
	v_lshlrev_b32_e32 v0, 16, v60
	v_and_b32_e32 v1, 0xffff0000, v60
	v_lshlrev_b32_e32 v2, 16, v61
	v_and_b32_e32 v3, 0xffff0000, v61
	s_waitcnt lgkmcnt(0)
	v_pk_mul_f32 v[0:1], v[4:5], v[0:1] op_sel_hi:[0,1]
	v_pk_mul_f32 v[2:3], v[4:5], v[2:3] op_sel_hi:[0,1]
	v_pk_mul_f32 v[6:7], v[4:5], v[6:7] op_sel_hi:[0,1]
	v_lshlrev_b32_e32 v10, 16, v63
	v_and_b32_e32 v11, 0xffff0000, v63
	v_pk_fma_f32 v[2:3], v[82:83], v[2:3], v[78:79]
	v_pk_fma_f32 v[0:1], v[80:81], v[0:1], v[76:77]
	v_pk_fma_f32 v[6:7], v[84:85], v[6:7], v[72:73]
	v_pk_mul_f32 v[10:11], v[4:5], v[10:11] op_sel_hi:[0,1]
	v_cvt_pk_bf16_f32 v0, v0, v1
	v_cvt_pk_bf16_f32 v1, v2, v3
	v_cvt_pk_bf16_f32 v2, v6, v7
	v_lshl_add_u64 v[6:7], s[10:11], 0, v[122:123]
	v_pk_fma_f32 v[10:11], v[86:87], v[10:11], v[74:75]
	v_lshl_add_u64 v[6:7], v[6:7], 0, v[8:9]
	v_cvt_pk_bf16_f32 v3, v10, v11
	ds_write_b128 v144, v[0:3]
	v_lshlrev_b32_e32 v8, 16, v38
	v_and_b32_e32 v9, 0xffff0000, v38
	v_lshlrev_b32_e32 v0, 16, v36
	v_and_b32_e32 v1, 0xffff0000, v36
	v_lshlrev_b32_e32 v2, 16, v37
	v_and_b32_e32 v3, 0xffff0000, v37
	v_lshlrev_b32_e32 v10, 16, v39
	v_and_b32_e32 v11, 0xffff0000, v39
	v_pk_mul_f32 v[0:1], v[4:5], v[0:1] op_sel_hi:[0,1]
	v_pk_mul_f32 v[2:3], v[4:5], v[2:3] op_sel_hi:[0,1]
	v_pk_fma_f32 v[2:3], v[98:99], v[2:3], v[66:67]
	v_pk_fma_f32 v[0:1], v[96:97], v[0:1], v[64:65]
	v_pk_mul_f32 v[8:9], v[4:5], v[8:9] op_sel_hi:[0,1]
	v_pk_mul_f32 v[4:5], v[4:5], v[10:11] op_sel_hi:[0,1]
	v_pk_fma_f32 v[4:5], v[102:103], v[4:5], v[42:43]
	v_pk_fma_f32 v[8:9], v[100:101], v[8:9], v[40:41]
	v_cvt_pk_bf16_f32 v0, v0, v1
	v_cvt_pk_bf16_f32 v1, v2, v3
	s_nop 0
	v_cvt_pk_bf16_f32 v2, v8, v9
	v_cvt_pk_bf16_f32 v3, v4, v5
	ds_write_b128 v144, v[0:3] offset:256
	v_lshl_add_u64 v[150:151], v[6:7], 0, v[148:149]
	s_waitcnt lgkmcnt(0)
	s_barrier
	ds_read_b128 v[168:171], v145
	ds_read_b128 v[172:175], v146
	s_waitcnt lgkmcnt(0)
	s_barrier
	global_store_dwordx4 v[150:151], v[168:171], off offset:-2048
	global_store_dwordx4 v[150:151], v[172:175], off offset:2048
	s_cbranch_vccnz .LBB0_1471
	s_andn2_b64 vcc, exec, s[8:9]
	s_cbranch_vccnz .LBB0_1470
	s_barrier
	s_branch .LBB0_1470
